# MFMA order: 16 chains per block walked column-wise over (bj,n) with a snake over m, so 12 of 15 chain boundaries share the weight fragment (srcA); on top of v56
# speedup vs baseline: 1.0027x; 1.0006x over previous
.LBB0_127:
	s_add_u32 s12, s52, 0xfff00080
	s_addc_u32 s13, s53, -1
	s_add_i32 s57, 0, 0x10000
	s_cmp_eq_u32 s56, 60
	s_cselect_b32 s15, s18, s13
	s_cselect_b32 s14, s19, s12
	v_add_u32_e32 v142, s57, v143
	s_cselect_b32 s13, s45, s55
	s_cselect_b32 s12, s47, s54
	s_add_i32 s60, 0, 0x14000
	ds_read_b128 v[146:149], v142
	ds_read_b128 v[152:155], v142 offset:1024
	ds_read_b128 v[156:159], v142 offset:2048
	ds_read_b128 v[160:163], v142 offset:3072
	v_add_u32_e32 v142, s60, v143
	ds_read_b128 v[164:167], v142
	ds_read_b128 v[168:171], v142 offset:1024
	ds_read_b128 v[172:175], v142 offset:2048
	ds_read_b128 v[176:179], v142 offset:3072
	v_lshl_add_u64 v[192:193], s[52:53], 0, v[138:139]
	s_add_i32 m0, s27, 0xc000
	ds_read_b128 v[180:183], v151
	ds_read_b128 v[184:187], v151 offset:1024
	ds_read_b128 v[188:191], v151 offset:2048
	ds_read_b128 v[206:209], v151 offset:3072
	ds_read_b128 v[210:213], v151 offset:4096
	ds_read_b128 v[240:243], v151 offset:5120
	ds_read_b128 v[244:247], v151 offset:6144
	ds_read_b128 v[248:251], v151 offset:7168
	global_load_lds_dwordx4 v[192:193], off
	v_lshl_add_u64 v[192:193], s[52:53], 0, v[140:141]
	s_add_i32 m0, s27, 0xe000
	s_nop 0
	global_load_lds_dwordx4 v[192:193], off
	s_waitcnt vmcnt(8)
	s_waitcnt lgkmcnt(0)
	s_barrier
	s_waitcnt lgkmcnt(0)
	v_mfma_f32_16x16x32_bf16 v[128:131], v[146:149], v[180:183], v[128:131]
	v_mfma_f32_16x16x32_bf16 v[128:131], v[152:155], v[184:187], v[128:131]
	v_mfma_f32_16x16x32_bf16 v[112:115], v[152:155], v[206:209], v[112:115]
	v_mfma_f32_16x16x32_bf16 v[112:115], v[146:149], v[188:191], v[112:115]
	v_mfma_f32_16x16x32_bf16 v[96:99], v[146:149], v[210:213], v[96:99]
	v_mfma_f32_16x16x32_bf16 v[96:99], v[152:155], v[240:243], v[96:99]
	v_mfma_f32_16x16x32_bf16 v[80:83], v[152:155], v[248:251], v[80:83]
	v_mfma_f32_16x16x32_bf16 v[80:83], v[146:149], v[244:247], v[80:83]
	v_mfma_f32_16x16x32_bf16 v[76:79], v[156:159], v[244:247], v[76:79]
	v_mfma_f32_16x16x32_bf16 v[76:79], v[160:163], v[248:251], v[76:79]
	v_mfma_f32_16x16x32_bf16 v[92:95], v[160:163], v[240:243], v[92:95]
	v_mfma_f32_16x16x32_bf16 v[92:95], v[156:159], v[210:213], v[92:95]
	v_mfma_f32_16x16x32_bf16 v[108:111], v[156:159], v[188:191], v[108:111]
	v_mfma_f32_16x16x32_bf16 v[108:111], v[160:163], v[206:209], v[108:111]
	v_mfma_f32_16x16x32_bf16 v[124:127], v[160:163], v[184:187], v[124:127]
	v_mfma_f32_16x16x32_bf16 v[124:127], v[156:159], v[180:183], v[124:127]
	v_mfma_f32_16x16x32_bf16 v[116:119], v[172:175], v[180:183], v[116:119]
	v_mfma_f32_16x16x32_bf16 v[116:119], v[176:179], v[184:187], v[116:119]
	v_mfma_f32_16x16x32_bf16 v[100:103], v[176:179], v[206:209], v[100:103]
	v_mfma_f32_16x16x32_bf16 v[100:103], v[172:175], v[188:191], v[100:103]
	v_mfma_f32_16x16x32_bf16 v[84:87], v[172:175], v[210:213], v[84:87]
	v_mfma_f32_16x16x32_bf16 v[84:87], v[176:179], v[240:243], v[84:87]
	v_mfma_f32_16x16x32_bf16 v[68:71], v[176:179], v[248:251], v[68:71]
	v_mfma_f32_16x16x32_bf16 v[68:71], v[172:175], v[244:247], v[68:71]
	v_mfma_f32_16x16x32_bf16 v[72:75], v[164:167], v[244:247], v[72:75]
	v_mfma_f32_16x16x32_bf16 v[72:75], v[168:171], v[248:251], v[72:75]
	v_mfma_f32_16x16x32_bf16 v[88:91], v[168:171], v[240:243], v[88:91]
	v_mfma_f32_16x16x32_bf16 v[88:91], v[164:167], v[210:213], v[88:91]
	v_mfma_f32_16x16x32_bf16 v[104:107], v[164:167], v[188:191], v[104:107]
	v_mfma_f32_16x16x32_bf16 v[104:107], v[168:171], v[206:209], v[104:107]
	v_mfma_f32_16x16x32_bf16 v[120:123], v[168:171], v[184:187], v[120:123]
	v_mfma_f32_16x16x32_bf16 v[120:123], v[164:167], v[180:183], v[120:123]
	s_barrier
	s_add_i32 s57, s57, s26
	v_lshl_add_u64 v[192:193], s[12:13], 0, v[2:3]
	s_mov_b32 m0, s57
	ds_read_b128 v[180:183], v151 offset:16384
	ds_read_b128 v[184:187], v151 offset:17408
	ds_read_b128 v[188:191], v151 offset:18432
	ds_read_b128 v[206:209], v151 offset:19456
	ds_read_b128 v[210:213], v151 offset:20480
	ds_read_b128 v[240:243], v151 offset:21504
	ds_read_b128 v[244:247], v151 offset:22528
	ds_read_b128 v[248:251], v151 offset:23552
	global_load_lds_dwordx4 v[192:193], off
	s_add_i32 m0, s57, 0x2000
	s_add_u32 s58, s12, 0x100000
	v_lshl_add_u64 v[214:215], s[12:13], 0, v[132:133]
	s_addc_u32 s59, s13, 0
	s_add_i32 s57, s60, s26
	global_load_lds_dwordx4 v[214:215], off
	v_lshl_add_u64 v[224:225], s[58:59], 0, v[2:3]
	s_mov_b32 m0, s57
	v_lshl_add_u64 v[226:227], s[14:15], 0, v[134:135]
	global_load_lds_dwordx4 v[224:225], off
	v_lshl_add_u64 v[224:225], s[58:59], 0, v[132:133]
	s_add_i32 m0, s57, 0x2000
	s_nop 0
	global_load_lds_dwordx4 v[224:225], off
	v_lshl_add_u64 v[224:225], s[14:15], 0, v[136:137]
	s_mov_b32 m0, s27
	s_nop 0
	global_load_lds_dwordx4 v[224:225], off
	s_mov_b32 m0, s28
	s_nop 0
	global_load_lds_dwordx4 v[226:227], off
	s_waitcnt vmcnt(8)
	s_waitcnt lgkmcnt(0)
	s_barrier
	s_waitcnt lgkmcnt(0)
	v_mfma_f32_16x16x32_bf16 v[64:67], v[146:149], v[180:183], v[64:67]
	v_mfma_f32_16x16x32_bf16 v[64:67], v[152:155], v[184:187], v[64:67]
	v_mfma_f32_16x16x32_bf16 v[52:55], v[152:155], v[206:209], v[52:55]
	v_mfma_f32_16x16x32_bf16 v[52:55], v[146:149], v[188:191], v[52:55]
	v_mfma_f32_16x16x32_bf16 v[36:39], v[146:149], v[210:213], v[36:39]
	v_mfma_f32_16x16x32_bf16 v[36:39], v[152:155], v[240:243], v[36:39]
	v_mfma_f32_16x16x32_bf16 v[20:23], v[152:155], v[248:251], v[20:23]
	v_mfma_f32_16x16x32_bf16 v[20:23], v[146:149], v[244:247], v[20:23]
	v_mfma_f32_16x16x32_bf16 v[12:15], v[156:159], v[244:247], v[12:15]
	v_mfma_f32_16x16x32_bf16 v[12:15], v[160:163], v[248:251], v[12:15]
	v_mfma_f32_16x16x32_bf16 v[28:31], v[160:163], v[240:243], v[28:31]
	v_mfma_f32_16x16x32_bf16 v[28:31], v[156:159], v[210:213], v[28:31]
	v_mfma_f32_16x16x32_bf16 v[44:47], v[156:159], v[188:191], v[44:47]
	v_mfma_f32_16x16x32_bf16 v[44:47], v[160:163], v[206:209], v[44:47]
	v_mfma_f32_16x16x32_bf16 v[60:63], v[160:163], v[184:187], v[60:63]
	v_mfma_f32_16x16x32_bf16 v[60:63], v[156:159], v[180:183], v[60:63]
	v_mfma_f32_16x16x32_bf16 v[48:51], v[172:175], v[180:183], v[48:51]
	v_mfma_f32_16x16x32_bf16 v[48:51], v[176:179], v[184:187], v[48:51]
	v_mfma_f32_16x16x32_bf16 v[32:35], v[176:179], v[206:209], v[32:35]
	v_mfma_f32_16x16x32_bf16 v[32:35], v[172:175], v[188:191], v[32:35]
	v_mfma_f32_16x16x32_bf16 v[16:19], v[172:175], v[210:213], v[16:19]
	v_mfma_f32_16x16x32_bf16 v[16:19], v[176:179], v[240:243], v[16:19]
	v_mfma_f32_16x16x32_bf16 v[4:7], v[176:179], v[248:251], v[4:7]
	v_mfma_f32_16x16x32_bf16 v[4:7], v[172:175], v[244:247], v[4:7]
	v_mfma_f32_16x16x32_bf16 v[8:11], v[164:167], v[244:247], v[8:11]
	v_mfma_f32_16x16x32_bf16 v[8:11], v[168:171], v[248:251], v[8:11]
	v_mfma_f32_16x16x32_bf16 v[24:27], v[168:171], v[240:243], v[24:27]
	v_mfma_f32_16x16x32_bf16 v[24:27], v[164:167], v[210:213], v[24:27]
	v_mfma_f32_16x16x32_bf16 v[40:43], v[164:167], v[188:191], v[40:43]
	v_mfma_f32_16x16x32_bf16 v[40:43], v[168:171], v[206:209], v[40:43]
	v_mfma_f32_16x16x32_bf16 v[56:59], v[168:171], v[184:187], v[56:59]
	v_mfma_f32_16x16x32_bf16 v[56:59], v[164:167], v[180:183], v[56:59]
	s_barrier
	s_add_i32 s57, 0, 0x18000
	v_add_u32_e32 v142, s57, v143
	s_add_i32 s58, 0, 0x1c000
	ds_read_b128 v[146:149], v142
	ds_read_b128 v[152:155], v142 offset:1024
	ds_read_b128 v[156:159], v142 offset:2048
	ds_read_b128 v[160:163], v142 offset:3072
	v_add_u32_e32 v142, s58, v143
	ds_read_b128 v[164:167], v142
	ds_read_b128 v[168:171], v142 offset:1024
	ds_read_b128 v[172:175], v142 offset:2048
	ds_read_b128 v[176:179], v142 offset:3072
	s_add_u32 s14, s14, 0x100000
	s_addc_u32 s15, s15, 0
	s_mov_b32 m0, s29
	v_lshl_add_u64 v[228:229], s[14:15], 0, v[136:137]
	ds_read_b128 v[180:183], v151 offset:32768
	ds_read_b128 v[184:187], v151 offset:33792
	ds_read_b128 v[188:191], v151 offset:34816
	ds_read_b128 v[206:209], v151 offset:35840
	ds_read_b128 v[210:213], v151 offset:36864
	ds_read_b128 v[240:243], v151 offset:37888
	ds_read_b128 v[244:247], v151 offset:38912
	ds_read_b128 v[248:251], v151 offset:39936
	global_load_lds_dwordx4 v[228:229], off
	v_lshl_add_u64 v[228:229], s[14:15], 0, v[134:135]
	s_mov_b32 m0, s30
	s_nop 0
	global_load_lds_dwordx4 v[228:229], off
	s_waitcnt vmcnt(8)
	s_waitcnt lgkmcnt(0)
	s_barrier
	s_waitcnt lgkmcnt(0)
	v_mfma_f32_16x16x32_bf16 v[128:131], v[146:149], v[180:183], v[128:131]
	v_mfma_f32_16x16x32_bf16 v[128:131], v[152:155], v[184:187], v[128:131]
	v_mfma_f32_16x16x32_bf16 v[112:115], v[152:155], v[206:209], v[112:115]
	v_mfma_f32_16x16x32_bf16 v[112:115], v[146:149], v[188:191], v[112:115]
	v_mfma_f32_16x16x32_bf16 v[96:99], v[146:149], v[210:213], v[96:99]
	v_mfma_f32_16x16x32_bf16 v[96:99], v[152:155], v[240:243], v[96:99]
	v_mfma_f32_16x16x32_bf16 v[80:83], v[152:155], v[248:251], v[80:83]
	v_mfma_f32_16x16x32_bf16 v[80:83], v[146:149], v[244:247], v[80:83]
	v_mfma_f32_16x16x32_bf16 v[76:79], v[156:159], v[244:247], v[76:79]
	v_mfma_f32_16x16x32_bf16 v[76:79], v[160:163], v[248:251], v[76:79]
	v_mfma_f32_16x16x32_bf16 v[92:95], v[160:163], v[240:243], v[92:95]
	v_mfma_f32_16x16x32_bf16 v[92:95], v[156:159], v[210:213], v[92:95]
	v_mfma_f32_16x16x32_bf16 v[108:111], v[156:159], v[188:191], v[108:111]
	v_mfma_f32_16x16x32_bf16 v[108:111], v[160:163], v[206:209], v[108:111]
	v_mfma_f32_16x16x32_bf16 v[124:127], v[160:163], v[184:187], v[124:127]
	v_mfma_f32_16x16x32_bf16 v[124:127], v[156:159], v[180:183], v[124:127]
	v_mfma_f32_16x16x32_bf16 v[116:119], v[172:175], v[180:183], v[116:119]
	v_mfma_f32_16x16x32_bf16 v[116:119], v[176:179], v[184:187], v[116:119]
	v_mfma_f32_16x16x32_bf16 v[100:103], v[176:179], v[206:209], v[100:103]
	v_mfma_f32_16x16x32_bf16 v[100:103], v[172:175], v[188:191], v[100:103]
	v_mfma_f32_16x16x32_bf16 v[84:87], v[172:175], v[210:213], v[84:87]
	v_mfma_f32_16x16x32_bf16 v[84:87], v[176:179], v[240:243], v[84:87]
	v_mfma_f32_16x16x32_bf16 v[68:71], v[176:179], v[248:251], v[68:71]
	v_mfma_f32_16x16x32_bf16 v[68:71], v[172:175], v[244:247], v[68:71]
	v_mfma_f32_16x16x32_bf16 v[72:75], v[164:167], v[244:247], v[72:75]
	v_mfma_f32_16x16x32_bf16 v[72:75], v[168:171], v[248:251], v[72:75]
	v_mfma_f32_16x16x32_bf16 v[88:91], v[168:171], v[240:243], v[88:91]
	v_mfma_f32_16x16x32_bf16 v[88:91], v[164:167], v[210:213], v[88:91]
	v_mfma_f32_16x16x32_bf16 v[104:107], v[164:167], v[188:191], v[104:107]
	v_mfma_f32_16x16x32_bf16 v[104:107], v[168:171], v[206:209], v[104:107]
	v_mfma_f32_16x16x32_bf16 v[120:123], v[168:171], v[184:187], v[120:123]
	v_mfma_f32_16x16x32_bf16 v[120:123], v[164:167], v[180:183], v[120:123]
	s_barrier
	s_add_i32 s14, s57, s26
	v_lshl_add_u64 v[192:193], v[192:193], 0, s[4:5]
	s_mov_b32 m0, s14
	ds_read_b128 v[180:183], v151 offset:49152
	ds_read_b128 v[184:187], v151 offset:50176
	ds_read_b128 v[188:191], v151 offset:51200
	ds_read_b128 v[206:209], v151 offset:52224
	ds_read_b128 v[210:213], v151 offset:53248
	ds_read_b128 v[240:243], v151 offset:54272
	ds_read_b128 v[244:247], v151 offset:55296
	ds_read_b128 v[248:251], v151 offset:56320
	global_load_lds_dwordx4 v[192:193], off
	s_add_i32 m0, s14, 0x2000
	s_add_u32 s12, s12, 0x100080
	v_lshl_add_u64 v[192:193], v[214:215], 0, s[4:5]
	s_addc_u32 s13, s13, 0
	s_add_i32 s14, s58, s26
	global_load_lds_dwordx4 v[192:193], off
	v_lshl_add_u64 v[192:193], s[12:13], 0, v[2:3]
	s_mov_b32 m0, s14
	s_nop 0
	global_load_lds_dwordx4 v[192:193], off
	v_lshl_add_u64 v[192:193], s[12:13], 0, v[132:133]
	s_add_i32 m0, s14, 0x2000
	s_nop 0
	global_load_lds_dwordx4 v[192:193], off
	v_lshl_add_u64 v[192:193], v[224:225], 0, s[4:5]
	s_mov_b32 m0, s31
	s_nop 0
	global_load_lds_dwordx4 v[192:193], off
	v_lshl_add_u64 v[192:193], v[226:227], 0, s[4:5]
	s_mov_b32 m0, s34
	s_nop 0
	global_load_lds_dwordx4 v[192:193], off
	s_waitcnt vmcnt(8)
	s_waitcnt lgkmcnt(0)
	s_barrier
	s_waitcnt lgkmcnt(0)
	v_mfma_f32_16x16x32_bf16 v[64:67], v[146:149], v[180:183], v[64:67]
	v_mfma_f32_16x16x32_bf16 v[64:67], v[152:155], v[184:187], v[64:67]
	v_mfma_f32_16x16x32_bf16 v[52:55], v[152:155], v[206:209], v[52:55]
	v_mfma_f32_16x16x32_bf16 v[52:55], v[146:149], v[188:191], v[52:55]
	v_mfma_f32_16x16x32_bf16 v[36:39], v[146:149], v[210:213], v[36:39]
	v_mfma_f32_16x16x32_bf16 v[36:39], v[152:155], v[240:243], v[36:39]
	v_mfma_f32_16x16x32_bf16 v[20:23], v[152:155], v[248:251], v[20:23]
	v_mfma_f32_16x16x32_bf16 v[20:23], v[146:149], v[244:247], v[20:23]
	v_mfma_f32_16x16x32_bf16 v[12:15], v[156:159], v[244:247], v[12:15]
	v_mfma_f32_16x16x32_bf16 v[12:15], v[160:163], v[248:251], v[12:15]
	v_mfma_f32_16x16x32_bf16 v[28:31], v[160:163], v[240:243], v[28:31]
	v_mfma_f32_16x16x32_bf16 v[28:31], v[156:159], v[210:213], v[28:31]
	v_mfma_f32_16x16x32_bf16 v[44:47], v[156:159], v[188:191], v[44:47]
	v_mfma_f32_16x16x32_bf16 v[44:47], v[160:163], v[206:209], v[44:47]
	v_mfma_f32_16x16x32_bf16 v[60:63], v[160:163], v[184:187], v[60:63]
	v_mfma_f32_16x16x32_bf16 v[60:63], v[156:159], v[180:183], v[60:63]
	v_mfma_f32_16x16x32_bf16 v[48:51], v[172:175], v[180:183], v[48:51]
	v_mfma_f32_16x16x32_bf16 v[48:51], v[176:179], v[184:187], v[48:51]
	v_mfma_f32_16x16x32_bf16 v[32:35], v[176:179], v[206:209], v[32:35]
	v_mfma_f32_16x16x32_bf16 v[32:35], v[172:175], v[188:191], v[32:35]
	v_mfma_f32_16x16x32_bf16 v[16:19], v[172:175], v[210:213], v[16:19]
	v_mfma_f32_16x16x32_bf16 v[16:19], v[176:179], v[240:243], v[16:19]
	v_mfma_f32_16x16x32_bf16 v[4:7], v[176:179], v[248:251], v[4:7]
	v_mfma_f32_16x16x32_bf16 v[4:7], v[172:175], v[244:247], v[4:7]
	v_mfma_f32_16x16x32_bf16 v[8:11], v[164:167], v[244:247], v[8:11]
	v_mfma_f32_16x16x32_bf16 v[8:11], v[168:171], v[248:251], v[8:11]
	v_mfma_f32_16x16x32_bf16 v[24:27], v[168:171], v[240:243], v[24:27]
	v_mfma_f32_16x16x32_bf16 v[24:27], v[164:167], v[210:213], v[24:27]
	v_mfma_f32_16x16x32_bf16 v[40:43], v[164:167], v[188:191], v[40:43]
	v_mfma_f32_16x16x32_bf16 v[40:43], v[168:171], v[206:209], v[40:43]
	v_mfma_f32_16x16x32_bf16 v[56:59], v[168:171], v[184:187], v[56:59]
	v_mfma_f32_16x16x32_bf16 v[56:59], v[164:167], v[180:183], v[56:59]
	s_barrier
	s_add_i32 s56, s56, 2
	s_add_u32 s52, s52, 0x100
	s_addc_u32 s53, s53, 0
	s_add_u32 s54, s54, 0x100
	s_addc_u32 s55, s55, 0
	s_cmp_gt_u32 s56, 61
	s_cbranch_scc0 .LBB0_127
	s_and_b64 vcc, exec, s[42:43]
	s_cbranch_vccz .LBB0_130
	s_barrier

.LBB0_1013:
	s_add_u32 s14, s60, 0x100
	s_addc_u32 s15, s61, 0
	s_add_i32 s70, 0, 0x10000
	s_cmp_eq_u32 s69, 60
	s_cselect_b32 s25, s3, s15
	s_cselect_b32 s24, s28, s14
	s_cselect_b32 s19, s29, s68
	s_cselect_b32 s18, s53, s55
	s_add_i32 s71, 0, 0x14000
	v_add_u32_e32 v64, s70, v178
	v_add_u32_e32 v160, s71, v178
	ds_read_b128 v[48:51], v64
	ds_read_b128 v[56:59], v64 offset:1024
	ds_read_b128 v[60:63], v64 offset:2048
	ds_read_b128 v[64:67], v64 offset:3072
	ds_read_b128 v[148:151], v160
	ds_read_b128 v[152:155], v160 offset:1024
	ds_read_b128 v[156:159], v160 offset:2048
	ds_read_b128 v[160:163], v160 offset:3072
	v_lshl_add_u64 v[214:215], s[60:61], 0, v[166:167]
	s_add_i32 m0, s36, 0xc000
	ds_read_b128 v[170:173], v180
	ds_read_b128 v[174:177], v180 offset:1024
	ds_read_b128 v[182:185], v180 offset:2048
	ds_read_b128 v[186:189], v180 offset:3072
	ds_read_b128 v[190:193], v180 offset:4096
	ds_read_b128 v[206:209], v180 offset:5120
	ds_read_b128 v[210:213], v180 offset:6144
	ds_read_b128 v[224:227], v180 offset:7168
	global_load_lds_dwordx4 v[214:215], off
	v_lshl_add_u64 v[214:215], s[60:61], 0, v[168:169]
	s_add_i32 m0, s36, 0xe000
	s_nop 0
	global_load_lds_dwordx4 v[214:215], off
	s_waitcnt vmcnt(8)
	s_waitcnt lgkmcnt(0)
	s_barrier
	s_waitcnt lgkmcnt(0)
	v_mfma_f32_16x16x32_bf16 v[144:147], v[48:51], v[170:173], v[144:147]
	v_mfma_f32_16x16x32_bf16 v[144:147], v[56:59], v[174:177], v[144:147]
	v_mfma_f32_16x16x32_bf16 v[128:131], v[56:59], v[186:189], v[128:131]
	v_mfma_f32_16x16x32_bf16 v[128:131], v[48:51], v[182:185], v[128:131]
	v_mfma_f32_16x16x32_bf16 v[112:115], v[48:51], v[190:193], v[112:115]
	v_mfma_f32_16x16x32_bf16 v[112:115], v[56:59], v[206:209], v[112:115]
	v_mfma_f32_16x16x32_bf16 v[96:99], v[56:59], v[224:227], v[96:99]
	v_mfma_f32_16x16x32_bf16 v[96:99], v[48:51], v[210:213], v[96:99]
	v_mfma_f32_16x16x32_bf16 v[92:95], v[60:63], v[210:213], v[92:95]
	v_mfma_f32_16x16x32_bf16 v[92:95], v[64:67], v[224:227], v[92:95]
	v_mfma_f32_16x16x32_bf16 v[108:111], v[64:67], v[206:209], v[108:111]
	v_mfma_f32_16x16x32_bf16 v[108:111], v[60:63], v[190:193], v[108:111]
	v_mfma_f32_16x16x32_bf16 v[124:127], v[60:63], v[182:185], v[124:127]
	v_mfma_f32_16x16x32_bf16 v[124:127], v[64:67], v[186:189], v[124:127]
	v_mfma_f32_16x16x32_bf16 v[140:143], v[64:67], v[174:177], v[140:143]
	v_mfma_f32_16x16x32_bf16 v[140:143], v[60:63], v[170:173], v[140:143]
	v_mfma_f32_16x16x32_bf16 v[132:135], v[156:159], v[170:173], v[132:135]
	v_mfma_f32_16x16x32_bf16 v[132:135], v[160:163], v[174:177], v[132:135]
	v_mfma_f32_16x16x32_bf16 v[116:119], v[160:163], v[186:189], v[116:119]
	v_mfma_f32_16x16x32_bf16 v[116:119], v[156:159], v[182:185], v[116:119]
	v_mfma_f32_16x16x32_bf16 v[100:103], v[156:159], v[190:193], v[100:103]
	v_mfma_f32_16x16x32_bf16 v[100:103], v[160:163], v[206:209], v[100:103]
	v_mfma_f32_16x16x32_bf16 v[84:87], v[160:163], v[224:227], v[84:87]
	v_mfma_f32_16x16x32_bf16 v[84:87], v[156:159], v[210:213], v[84:87]
	v_mfma_f32_16x16x32_bf16 v[88:91], v[148:151], v[210:213], v[88:91]
	v_mfma_f32_16x16x32_bf16 v[88:91], v[152:155], v[224:227], v[88:91]
	v_mfma_f32_16x16x32_bf16 v[104:107], v[152:155], v[206:209], v[104:107]
	v_mfma_f32_16x16x32_bf16 v[104:107], v[148:151], v[190:193], v[104:107]
	v_mfma_f32_16x16x32_bf16 v[120:123], v[148:151], v[182:185], v[120:123]
	v_mfma_f32_16x16x32_bf16 v[120:123], v[152:155], v[186:189], v[120:123]
	v_mfma_f32_16x16x32_bf16 v[136:139], v[152:155], v[174:177], v[136:139]
	v_mfma_f32_16x16x32_bf16 v[136:139], v[148:151], v[170:173], v[136:139]
	s_barrier
	s_add_i32 s60, s70, s35
	v_lshl_add_u64 v[214:215], s[18:19], 0, v[2:3]
	s_mov_b32 m0, s60
	ds_read_b128 v[170:173], v180 offset:16384
	ds_read_b128 v[174:177], v180 offset:17408
	ds_read_b128 v[182:185], v180 offset:18432
	ds_read_b128 v[186:189], v180 offset:19456
	ds_read_b128 v[190:193], v180 offset:20480
	ds_read_b128 v[206:209], v180 offset:21504
	ds_read_b128 v[210:213], v180 offset:22528
	ds_read_b128 v[224:227], v180 offset:23552
	global_load_lds_dwordx4 v[214:215], off
	s_add_i32 m0, s60, 0x2000
	s_add_u32 s60, s18, 0x100000
	v_lshl_add_u64 v[228:229], s[18:19], 0, v[164:165]
	s_addc_u32 s61, s19, 0
	s_add_i32 s70, s71, s35
	global_load_lds_dwordx4 v[228:229], off
	v_lshl_add_u64 v[230:231], s[60:61], 0, v[2:3]
	s_mov_b32 m0, s70
	v_lshl_add_u64 v[240:241], s[24:25], 0, v[164:165]
	global_load_lds_dwordx4 v[230:231], off
	v_lshl_add_u64 v[230:231], s[60:61], 0, v[164:165]
	s_add_i32 m0, s70, 0x2000
	s_nop 0
	global_load_lds_dwordx4 v[230:231], off
	v_lshl_add_u64 v[230:231], s[24:25], 0, v[2:3]
	s_mov_b32 m0, s36
	s_nop 0
	global_load_lds_dwordx4 v[230:231], off
	s_mov_b32 m0, s37
	s_nop 0
	global_load_lds_dwordx4 v[240:241], off
	s_waitcnt vmcnt(8)
	s_waitcnt lgkmcnt(0)
	s_barrier
	s_waitcnt lgkmcnt(0)
	v_mfma_f32_16x16x32_bf16 v[80:83], v[48:51], v[170:173], v[80:83]
	v_mfma_f32_16x16x32_bf16 v[80:83], v[56:59], v[174:177], v[80:83]
	v_mfma_f32_16x16x32_bf16 v[52:55], v[56:59], v[186:189], v[52:55]
	v_mfma_f32_16x16x32_bf16 v[52:55], v[48:51], v[182:185], v[52:55]
	v_mfma_f32_16x16x32_bf16 v[32:35], v[48:51], v[190:193], v[32:35]
	v_mfma_f32_16x16x32_bf16 v[32:35], v[56:59], v[206:209], v[32:35]
	v_mfma_f32_16x16x32_bf16 v[16:19], v[56:59], v[224:227], v[16:19]
	v_mfma_f32_16x16x32_bf16 v[16:19], v[48:51], v[210:213], v[16:19]
	v_mfma_f32_16x16x32_bf16 v[12:15], v[60:63], v[210:213], v[12:15]
	v_mfma_f32_16x16x32_bf16 v[12:15], v[64:67], v[224:227], v[12:15]
	v_mfma_f32_16x16x32_bf16 v[28:31], v[64:67], v[206:209], v[28:31]
	v_mfma_f32_16x16x32_bf16 v[28:31], v[60:63], v[190:193], v[28:31]
	v_mfma_f32_16x16x32_bf16 v[44:47], v[60:63], v[182:185], v[44:47]
	v_mfma_f32_16x16x32_bf16 v[44:47], v[64:67], v[186:189], v[44:47]
	v_mfma_f32_16x16x32_bf16 v[76:79], v[64:67], v[174:177], v[76:79]
	v_mfma_f32_16x16x32_bf16 v[76:79], v[60:63], v[170:173], v[76:79]
	v_mfma_f32_16x16x32_bf16 v[36:39], v[156:159], v[182:185], v[36:39]
	v_mfma_f32_16x16x32_bf16 v[36:39], v[160:163], v[186:189], v[36:39]
	v_mfma_f32_16x16x32_bf16 v[20:23], v[160:163], v[206:209], v[20:23]
	v_mfma_f32_16x16x32_bf16 v[20:23], v[156:159], v[190:193], v[20:23]
	v_mfma_f32_16x16x32_bf16 v[4:7], v[156:159], v[210:213], v[4:7]
	v_mfma_f32_16x16x32_bf16 v[4:7], v[160:163], v[224:227], v[4:7]
	v_mfma_f32_16x16x32_bf16 v[56:59], v[156:159], v[170:173], v[68:71]
	v_mfma_f32_16x16x32_bf16 v[56:59], v[160:163], v[174:177], v[56:59]
	v_mfma_f32_16x16x32_bf16 v[48:51], v[148:151], v[170:173], v[72:75]
	v_mfma_f32_16x16x32_bf16 v[48:51], v[152:155], v[174:177], v[48:51]
	v_mfma_f32_16x16x32_bf16 v[8:11], v[152:155], v[224:227], v[8:11]
	v_mfma_f32_16x16x32_bf16 v[8:11], v[148:151], v[210:213], v[8:11]
	v_mfma_f32_16x16x32_bf16 v[24:27], v[148:151], v[190:193], v[24:27]
	v_mfma_f32_16x16x32_bf16 v[24:27], v[152:155], v[206:209], v[24:27]
	v_mfma_f32_16x16x32_bf16 v[40:43], v[152:155], v[186:189], v[40:43]
	v_mfma_f32_16x16x32_bf16 v[40:43], v[148:151], v[182:185], v[40:43]
	s_barrier
	s_add_i32 s60, 0, 0x18000
	s_add_i32 s61, 0, 0x1c000
	v_add_u32_e32 v72, s60, v178
	v_add_u32_e32 v160, s61, v178
	ds_read_b128 v[60:63], v72
	ds_read_b128 v[64:67], v72 offset:1024
	ds_read_b128 v[68:71], v72 offset:2048
	ds_read_b128 v[72:75], v72 offset:3072
	ds_read_b128 v[148:151], v160
	ds_read_b128 v[152:155], v160 offset:1024
	ds_read_b128 v[156:159], v160 offset:2048
	ds_read_b128 v[160:163], v160 offset:3072
	s_add_u32 s24, s24, 0x100000
	s_addc_u32 s25, s25, 0
	s_mov_b32 m0, s62
	v_lshl_add_u64 v[242:243], s[24:25], 0, v[2:3]
	ds_read_b128 v[170:173], v180 offset:32768
	ds_read_b128 v[174:177], v180 offset:33792
	ds_read_b128 v[182:185], v180 offset:34816
	ds_read_b128 v[186:189], v180 offset:35840
	ds_read_b128 v[190:193], v180 offset:36864
	ds_read_b128 v[206:209], v180 offset:37888
	ds_read_b128 v[210:213], v180 offset:38912
	ds_read_b128 v[224:227], v180 offset:39936
	global_load_lds_dwordx4 v[242:243], off
	v_lshl_add_u64 v[242:243], s[24:25], 0, v[164:165]
	s_mov_b32 m0, s63
	s_nop 0
	global_load_lds_dwordx4 v[242:243], off
	s_waitcnt vmcnt(8)
	s_waitcnt lgkmcnt(0)
	s_barrier
	s_waitcnt lgkmcnt(0)
	v_mfma_f32_16x16x32_bf16 v[144:147], v[60:63], v[170:173], v[144:147]
	v_mfma_f32_16x16x32_bf16 v[144:147], v[64:67], v[174:177], v[144:147]
	v_mfma_f32_16x16x32_bf16 v[128:131], v[64:67], v[186:189], v[128:131]
	v_mfma_f32_16x16x32_bf16 v[128:131], v[60:63], v[182:185], v[128:131]
	v_mfma_f32_16x16x32_bf16 v[112:115], v[60:63], v[190:193], v[112:115]
	v_mfma_f32_16x16x32_bf16 v[112:115], v[64:67], v[206:209], v[112:115]
	v_mfma_f32_16x16x32_bf16 v[96:99], v[64:67], v[224:227], v[96:99]
	v_mfma_f32_16x16x32_bf16 v[96:99], v[60:63], v[210:213], v[96:99]
	v_mfma_f32_16x16x32_bf16 v[92:95], v[68:71], v[210:213], v[92:95]
	v_mfma_f32_16x16x32_bf16 v[92:95], v[72:75], v[224:227], v[92:95]
	v_mfma_f32_16x16x32_bf16 v[108:111], v[72:75], v[206:209], v[108:111]
	v_mfma_f32_16x16x32_bf16 v[108:111], v[68:71], v[190:193], v[108:111]
	v_mfma_f32_16x16x32_bf16 v[124:127], v[68:71], v[182:185], v[124:127]
	v_mfma_f32_16x16x32_bf16 v[124:127], v[72:75], v[186:189], v[124:127]
	v_mfma_f32_16x16x32_bf16 v[140:143], v[72:75], v[174:177], v[140:143]
	v_mfma_f32_16x16x32_bf16 v[140:143], v[68:71], v[170:173], v[140:143]
	v_mfma_f32_16x16x32_bf16 v[132:135], v[156:159], v[170:173], v[132:135]
	v_mfma_f32_16x16x32_bf16 v[132:135], v[160:163], v[174:177], v[132:135]
	v_mfma_f32_16x16x32_bf16 v[116:119], v[160:163], v[186:189], v[116:119]
	v_mfma_f32_16x16x32_bf16 v[116:119], v[156:159], v[182:185], v[116:119]
	v_mfma_f32_16x16x32_bf16 v[100:103], v[156:159], v[190:193], v[100:103]
	v_mfma_f32_16x16x32_bf16 v[100:103], v[160:163], v[206:209], v[100:103]
	v_mfma_f32_16x16x32_bf16 v[84:87], v[160:163], v[224:227], v[84:87]
	v_mfma_f32_16x16x32_bf16 v[84:87], v[156:159], v[210:213], v[84:87]
	v_mfma_f32_16x16x32_bf16 v[88:91], v[148:151], v[210:213], v[88:91]
	v_mfma_f32_16x16x32_bf16 v[88:91], v[152:155], v[224:227], v[88:91]
	v_mfma_f32_16x16x32_bf16 v[104:107], v[152:155], v[206:209], v[104:107]
	v_mfma_f32_16x16x32_bf16 v[104:107], v[148:151], v[190:193], v[104:107]
	v_mfma_f32_16x16x32_bf16 v[120:123], v[148:151], v[182:185], v[120:123]
	v_mfma_f32_16x16x32_bf16 v[120:123], v[152:155], v[186:189], v[120:123]
	v_mfma_f32_16x16x32_bf16 v[136:139], v[152:155], v[174:177], v[136:139]
	v_mfma_f32_16x16x32_bf16 v[136:139], v[148:151], v[170:173], v[136:139]
	s_barrier
	s_add_i32 s24, s60, s35
	v_lshl_add_u64 v[214:215], v[214:215], 0, s[4:5]
	s_mov_b32 m0, s24
	ds_read_b128 v[170:173], v180 offset:49152
	ds_read_b128 v[174:177], v180 offset:50176
	ds_read_b128 v[182:185], v180 offset:51200
	ds_read_b128 v[186:189], v180 offset:52224
	ds_read_b128 v[190:193], v180 offset:53248
	ds_read_b128 v[206:209], v180 offset:54272
	ds_read_b128 v[210:213], v180 offset:55296
	ds_read_b128 v[224:227], v180 offset:56320
	global_load_lds_dwordx4 v[214:215], off
	s_add_i32 m0, s24, 0x2000
	s_add_u32 s18, s18, 0x100080
	v_lshl_add_u64 v[214:215], v[228:229], 0, s[4:5]
	s_addc_u32 s19, s19, 0
	s_add_i32 s24, s61, s35
	global_load_lds_dwordx4 v[214:215], off
	v_lshl_add_u64 v[214:215], s[18:19], 0, v[2:3]
	s_mov_b32 m0, s24
	s_nop 0
	global_load_lds_dwordx4 v[214:215], off
	v_lshl_add_u64 v[214:215], s[18:19], 0, v[164:165]
	s_add_i32 m0, s24, 0x2000
	s_nop 0
	global_load_lds_dwordx4 v[214:215], off
	v_lshl_add_u64 v[214:215], v[230:231], 0, s[4:5]
	s_mov_b32 m0, s65
	s_nop 0
	global_load_lds_dwordx4 v[214:215], off
	v_lshl_add_u64 v[214:215], v[240:241], 0, s[4:5]
	s_mov_b32 m0, s66
	s_nop 0
	global_load_lds_dwordx4 v[214:215], off
	s_waitcnt vmcnt(8)
	s_waitcnt lgkmcnt(0)
	s_barrier
	s_waitcnt lgkmcnt(0)
	v_mfma_f32_16x16x32_bf16 v[80:83], v[60:63], v[170:173], v[80:83]
	v_mfma_f32_16x16x32_bf16 v[80:83], v[64:67], v[174:177], v[80:83]
	v_mfma_f32_16x16x32_bf16 v[76:79], v[72:75], v[174:177], v[76:79]
	v_mfma_f32_16x16x32_bf16 v[76:79], v[68:71], v[170:173], v[76:79]
	v_mfma_f32_16x16x32_bf16 v[44:47], v[68:71], v[182:185], v[44:47]
	v_mfma_f32_16x16x32_bf16 v[44:47], v[72:75], v[186:189], v[44:47]
	v_mfma_f32_16x16x32_bf16 v[52:55], v[64:67], v[186:189], v[52:55]
	v_mfma_f32_16x16x32_bf16 v[52:55], v[60:63], v[182:185], v[52:55]
	v_mfma_f32_16x16x32_bf16 v[32:35], v[60:63], v[190:193], v[32:35]
	v_mfma_f32_16x16x32_bf16 v[32:35], v[64:67], v[206:209], v[32:35]
	v_mfma_f32_16x16x32_bf16 v[28:31], v[72:75], v[206:209], v[28:31]
	v_mfma_f32_16x16x32_bf16 v[28:31], v[68:71], v[190:193], v[28:31]
	v_mfma_f32_16x16x32_bf16 v[12:15], v[68:71], v[210:213], v[12:15]
	v_mfma_f32_16x16x32_bf16 v[12:15], v[72:75], v[224:227], v[12:15]
	v_mfma_f32_16x16x32_bf16 v[16:19], v[64:67], v[224:227], v[16:19]
	v_mfma_f32_16x16x32_bf16 v[16:19], v[60:63], v[210:213], v[16:19]
	v_mfma_f32_16x16x32_bf16 v[48:51], v[148:151], v[170:173], v[48:51]
	v_mfma_f32_16x16x32_bf16 v[72:75], v[152:155], v[174:177], v[48:51]
	v_mfma_f32_16x16x32_bf16 v[48:51], v[156:159], v[170:173], v[56:59]
	v_mfma_f32_16x16x32_bf16 v[68:71], v[160:163], v[174:177], v[48:51]
	v_mfma_f32_16x16x32_bf16 v[36:39], v[160:163], v[186:189], v[36:39]
	v_mfma_f32_16x16x32_bf16 v[36:39], v[156:159], v[182:185], v[36:39]
	v_mfma_f32_16x16x32_bf16 v[40:43], v[148:151], v[182:185], v[40:43]
	v_mfma_f32_16x16x32_bf16 v[40:43], v[152:155], v[186:189], v[40:43]
	v_mfma_f32_16x16x32_bf16 v[24:27], v[152:155], v[206:209], v[24:27]
	v_mfma_f32_16x16x32_bf16 v[24:27], v[148:151], v[190:193], v[24:27]
	v_mfma_f32_16x16x32_bf16 v[20:23], v[156:159], v[190:193], v[20:23]
	v_mfma_f32_16x16x32_bf16 v[20:23], v[160:163], v[206:209], v[20:23]
	v_mfma_f32_16x16x32_bf16 v[4:7], v[160:163], v[224:227], v[4:7]
	v_mfma_f32_16x16x32_bf16 v[4:7], v[156:159], v[210:213], v[4:7]
	v_mfma_f32_16x16x32_bf16 v[8:11], v[148:151], v[210:213], v[8:11]
	v_mfma_f32_16x16x32_bf16 v[8:11], v[152:155], v[224:227], v[8:11]
	s_barrier
	s_add_i32 s69, s69, 2
	s_add_u32 s55, s55, 0x100
	s_addc_u32 s68, s68, 0
	s_cmp_gt_u32 s69, 61
	s_mov_b64 s[60:61], s[14:15]
	s_cbranch_scc0 .LBB0_1013
	s_and_b64 vcc, exec, s[50:51]
	s_cbranch_vccz .LBB0_1016
	s_barrier

.LBB0_1158:
	s_add_u32 s14, s52, 0xfff00080
	s_addc_u32 s15, s53, -1
	s_add_i32 s59, 0, 0x10000
	s_cmp_eq_u32 s47, 60
	s_cselect_b32 s19, s3, s15
	s_cselect_b32 s18, s24, s14
	v_add_u32_e32 v142, s59, v143
	s_cselect_b32 s15, s25, s45
	s_cselect_b32 s14, s28, s29
	s_add_i32 s62, 0, 0x14000
	ds_read_b128 v[144:147], v142
	ds_read_b128 v[152:155], v142 offset:1024
	ds_read_b128 v[156:159], v142 offset:2048
	ds_read_b128 v[160:163], v142 offset:3072
	v_add_u32_e32 v142, s62, v143
	ds_read_b128 v[164:167], v142
	ds_read_b128 v[168:171], v142 offset:1024
	ds_read_b128 v[172:175], v142 offset:2048
	ds_read_b128 v[176:179], v142 offset:3072
	v_lshl_add_u64 v[192:193], s[52:53], 0, v[138:139]
	s_add_i32 m0, s36, 0xc000
	ds_read_b128 v[180:183], v151
	ds_read_b128 v[184:187], v151 offset:1024
	ds_read_b128 v[188:191], v151 offset:2048
	ds_read_b128 v[206:209], v151 offset:3072
	ds_read_b128 v[210:213], v151 offset:4096
	ds_read_b128 v[224:227], v151 offset:5120
	ds_read_b128 v[228:231], v151 offset:6144
	ds_read_b128 v[240:243], v151 offset:7168
	global_load_lds_dwordx4 v[192:193], off
	v_lshl_add_u64 v[192:193], s[52:53], 0, v[140:141]
	s_add_i32 m0, s36, 0xe000
	s_nop 0
	global_load_lds_dwordx4 v[192:193], off
	s_waitcnt vmcnt(8)
	s_waitcnt lgkmcnt(0)
	s_barrier
	s_waitcnt lgkmcnt(0)
	v_mfma_f32_16x16x32_bf16 v[128:131], v[144:147], v[180:183], v[128:131]
	v_mfma_f32_16x16x32_bf16 v[128:131], v[152:155], v[184:187], v[128:131]
	v_mfma_f32_16x16x32_bf16 v[112:115], v[152:155], v[206:209], v[112:115]
	v_mfma_f32_16x16x32_bf16 v[112:115], v[144:147], v[188:191], v[112:115]
	v_mfma_f32_16x16x32_bf16 v[96:99], v[144:147], v[210:213], v[96:99]
	v_mfma_f32_16x16x32_bf16 v[96:99], v[152:155], v[224:227], v[96:99]
	v_mfma_f32_16x16x32_bf16 v[80:83], v[152:155], v[240:243], v[80:83]
	v_mfma_f32_16x16x32_bf16 v[80:83], v[144:147], v[228:231], v[80:83]
	v_mfma_f32_16x16x32_bf16 v[76:79], v[156:159], v[228:231], v[76:79]
	v_mfma_f32_16x16x32_bf16 v[76:79], v[160:163], v[240:243], v[76:79]
	v_mfma_f32_16x16x32_bf16 v[92:95], v[160:163], v[224:227], v[92:95]
	v_mfma_f32_16x16x32_bf16 v[92:95], v[156:159], v[210:213], v[92:95]
	v_mfma_f32_16x16x32_bf16 v[108:111], v[156:159], v[188:191], v[108:111]
	v_mfma_f32_16x16x32_bf16 v[108:111], v[160:163], v[206:209], v[108:111]
	v_mfma_f32_16x16x32_bf16 v[124:127], v[160:163], v[184:187], v[124:127]
	v_mfma_f32_16x16x32_bf16 v[124:127], v[156:159], v[180:183], v[124:127]
	v_mfma_f32_16x16x32_bf16 v[116:119], v[172:175], v[180:183], v[116:119]
	v_mfma_f32_16x16x32_bf16 v[116:119], v[176:179], v[184:187], v[116:119]
	v_mfma_f32_16x16x32_bf16 v[100:103], v[176:179], v[206:209], v[100:103]
	v_mfma_f32_16x16x32_bf16 v[100:103], v[172:175], v[188:191], v[100:103]
	v_mfma_f32_16x16x32_bf16 v[84:87], v[172:175], v[210:213], v[84:87]
	v_mfma_f32_16x16x32_bf16 v[84:87], v[176:179], v[224:227], v[84:87]
	v_mfma_f32_16x16x32_bf16 v[68:71], v[176:179], v[240:243], v[68:71]
	v_mfma_f32_16x16x32_bf16 v[68:71], v[172:175], v[228:231], v[68:71]
	v_mfma_f32_16x16x32_bf16 v[72:75], v[164:167], v[228:231], v[72:75]
	v_mfma_f32_16x16x32_bf16 v[72:75], v[168:171], v[240:243], v[72:75]
	v_mfma_f32_16x16x32_bf16 v[88:91], v[168:171], v[224:227], v[88:91]
	v_mfma_f32_16x16x32_bf16 v[88:91], v[164:167], v[210:213], v[88:91]
	v_mfma_f32_16x16x32_bf16 v[104:107], v[164:167], v[188:191], v[104:107]
	v_mfma_f32_16x16x32_bf16 v[104:107], v[168:171], v[206:209], v[104:107]
	v_mfma_f32_16x16x32_bf16 v[120:123], v[168:171], v[184:187], v[120:123]
	v_mfma_f32_16x16x32_bf16 v[120:123], v[164:167], v[180:183], v[120:123]
	s_barrier
	s_add_i32 s59, s59, s35
	v_lshl_add_u64 v[192:193], s[14:15], 0, v[2:3]
	s_mov_b32 m0, s59
	ds_read_b128 v[180:183], v151 offset:16384
	ds_read_b128 v[184:187], v151 offset:17408
	ds_read_b128 v[188:191], v151 offset:18432
	ds_read_b128 v[206:209], v151 offset:19456
	ds_read_b128 v[210:213], v151 offset:20480
	ds_read_b128 v[224:227], v151 offset:21504
	ds_read_b128 v[228:231], v151 offset:22528
	ds_read_b128 v[240:243], v151 offset:23552
	global_load_lds_dwordx4 v[192:193], off
	s_add_i32 m0, s59, 0x2000
	s_add_u32 s60, s14, 0x100000
	v_lshl_add_u64 v[214:215], s[14:15], 0, v[132:133]
	s_addc_u32 s61, s15, 0
	s_add_i32 s59, s62, s35
	global_load_lds_dwordx4 v[214:215], off
	v_lshl_add_u64 v[244:245], s[60:61], 0, v[2:3]
	s_mov_b32 m0, s59
	v_lshl_add_u64 v[246:247], s[18:19], 0, v[134:135]
	global_load_lds_dwordx4 v[244:245], off
	v_lshl_add_u64 v[244:245], s[60:61], 0, v[132:133]
	s_add_i32 m0, s59, 0x2000
	s_nop 0
	global_load_lds_dwordx4 v[244:245], off
	v_lshl_add_u64 v[244:245], s[18:19], 0, v[136:137]
	s_mov_b32 m0, s36
	s_nop 0
	global_load_lds_dwordx4 v[244:245], off
	s_mov_b32 m0, s37
	s_nop 0
	global_load_lds_dwordx4 v[246:247], off
	s_waitcnt vmcnt(8)
	s_waitcnt lgkmcnt(0)
	s_barrier
	s_waitcnt lgkmcnt(0)
	v_mfma_f32_16x16x32_bf16 v[64:67], v[144:147], v[180:183], v[64:67]
	v_mfma_f32_16x16x32_bf16 v[64:67], v[152:155], v[184:187], v[64:67]
	v_mfma_f32_16x16x32_bf16 v[48:51], v[152:155], v[206:209], v[48:51]
	v_mfma_f32_16x16x32_bf16 v[48:51], v[144:147], v[188:191], v[48:51]
	v_mfma_f32_16x16x32_bf16 v[32:35], v[144:147], v[210:213], v[32:35]
	v_mfma_f32_16x16x32_bf16 v[32:35], v[152:155], v[224:227], v[32:35]
	v_mfma_f32_16x16x32_bf16 v[16:19], v[152:155], v[240:243], v[16:19]
	v_mfma_f32_16x16x32_bf16 v[16:19], v[144:147], v[228:231], v[16:19]
	v_mfma_f32_16x16x32_bf16 v[12:15], v[156:159], v[228:231], v[12:15]
	v_mfma_f32_16x16x32_bf16 v[12:15], v[160:163], v[240:243], v[12:15]
	v_mfma_f32_16x16x32_bf16 v[28:31], v[160:163], v[224:227], v[28:31]
	v_mfma_f32_16x16x32_bf16 v[28:31], v[156:159], v[210:213], v[28:31]
	v_mfma_f32_16x16x32_bf16 v[44:47], v[156:159], v[188:191], v[44:47]
	v_mfma_f32_16x16x32_bf16 v[44:47], v[160:163], v[206:209], v[44:47]
	v_mfma_f32_16x16x32_bf16 v[60:63], v[160:163], v[184:187], v[60:63]
	v_mfma_f32_16x16x32_bf16 v[60:63], v[156:159], v[180:183], v[60:63]
	v_mfma_f32_16x16x32_bf16 v[52:55], v[172:175], v[180:183], v[52:55]
	v_mfma_f32_16x16x32_bf16 v[52:55], v[176:179], v[184:187], v[52:55]
	v_mfma_f32_16x16x32_bf16 v[36:39], v[176:179], v[206:209], v[36:39]
	v_mfma_f32_16x16x32_bf16 v[36:39], v[172:175], v[188:191], v[36:39]
	v_mfma_f32_16x16x32_bf16 v[20:23], v[172:175], v[210:213], v[20:23]
	v_mfma_f32_16x16x32_bf16 v[20:23], v[176:179], v[224:227], v[20:23]
	v_mfma_f32_16x16x32_bf16 v[4:7], v[176:179], v[240:243], v[4:7]
	v_mfma_f32_16x16x32_bf16 v[4:7], v[172:175], v[228:231], v[4:7]
	v_mfma_f32_16x16x32_bf16 v[8:11], v[164:167], v[228:231], v[8:11]
	v_mfma_f32_16x16x32_bf16 v[8:11], v[168:171], v[240:243], v[8:11]
	v_mfma_f32_16x16x32_bf16 v[24:27], v[168:171], v[224:227], v[24:27]
	v_mfma_f32_16x16x32_bf16 v[24:27], v[164:167], v[210:213], v[24:27]
	v_mfma_f32_16x16x32_bf16 v[40:43], v[164:167], v[188:191], v[40:43]
	v_mfma_f32_16x16x32_bf16 v[40:43], v[168:171], v[206:209], v[40:43]
	v_mfma_f32_16x16x32_bf16 v[56:59], v[168:171], v[184:187], v[56:59]
	v_mfma_f32_16x16x32_bf16 v[56:59], v[164:167], v[180:183], v[56:59]
	s_barrier
	s_add_i32 s59, 0, 0x18000
	v_add_u32_e32 v142, s59, v143
	s_add_i32 s60, 0, 0x1c000
	ds_read_b128 v[144:147], v142
	ds_read_b128 v[152:155], v142 offset:1024
	ds_read_b128 v[156:159], v142 offset:2048
	ds_read_b128 v[160:163], v142 offset:3072
	v_add_u32_e32 v142, s60, v143
	ds_read_b128 v[164:167], v142
	ds_read_b128 v[168:171], v142 offset:1024
	ds_read_b128 v[172:175], v142 offset:2048
	ds_read_b128 v[176:179], v142 offset:3072
	s_add_u32 s18, s18, 0x100000
	s_addc_u32 s19, s19, 0
	s_mov_b32 m0, s54
	v_lshl_add_u64 v[248:249], s[18:19], 0, v[136:137]
	ds_read_b128 v[180:183], v151 offset:32768
	ds_read_b128 v[184:187], v151 offset:33792
	ds_read_b128 v[188:191], v151 offset:34816
	ds_read_b128 v[206:209], v151 offset:35840
	ds_read_b128 v[210:213], v151 offset:36864
	ds_read_b128 v[224:227], v151 offset:37888
	ds_read_b128 v[228:231], v151 offset:38912
	ds_read_b128 v[240:243], v151 offset:39936
	global_load_lds_dwordx4 v[248:249], off
	v_lshl_add_u64 v[248:249], s[18:19], 0, v[134:135]
	s_mov_b32 m0, s55
	s_nop 0
	global_load_lds_dwordx4 v[248:249], off
	s_waitcnt vmcnt(8)
	s_waitcnt lgkmcnt(0)
	s_barrier
	s_waitcnt lgkmcnt(0)
	v_mfma_f32_16x16x32_bf16 v[128:131], v[144:147], v[180:183], v[128:131]
	v_mfma_f32_16x16x32_bf16 v[128:131], v[152:155], v[184:187], v[128:131]
	v_mfma_f32_16x16x32_bf16 v[112:115], v[152:155], v[206:209], v[112:115]
	v_mfma_f32_16x16x32_bf16 v[112:115], v[144:147], v[188:191], v[112:115]
	v_mfma_f32_16x16x32_bf16 v[96:99], v[144:147], v[210:213], v[96:99]
	v_mfma_f32_16x16x32_bf16 v[96:99], v[152:155], v[224:227], v[96:99]
	v_mfma_f32_16x16x32_bf16 v[80:83], v[152:155], v[240:243], v[80:83]
	v_mfma_f32_16x16x32_bf16 v[80:83], v[144:147], v[228:231], v[80:83]
	v_mfma_f32_16x16x32_bf16 v[76:79], v[156:159], v[228:231], v[76:79]
	v_mfma_f32_16x16x32_bf16 v[76:79], v[160:163], v[240:243], v[76:79]
	v_mfma_f32_16x16x32_bf16 v[92:95], v[160:163], v[224:227], v[92:95]
	v_mfma_f32_16x16x32_bf16 v[92:95], v[156:159], v[210:213], v[92:95]
	v_mfma_f32_16x16x32_bf16 v[108:111], v[156:159], v[188:191], v[108:111]
	v_mfma_f32_16x16x32_bf16 v[108:111], v[160:163], v[206:209], v[108:111]
	v_mfma_f32_16x16x32_bf16 v[124:127], v[160:163], v[184:187], v[124:127]
	v_mfma_f32_16x16x32_bf16 v[124:127], v[156:159], v[180:183], v[124:127]
	v_mfma_f32_16x16x32_bf16 v[116:119], v[172:175], v[180:183], v[116:119]
	v_mfma_f32_16x16x32_bf16 v[116:119], v[176:179], v[184:187], v[116:119]
	v_mfma_f32_16x16x32_bf16 v[100:103], v[176:179], v[206:209], v[100:103]
	v_mfma_f32_16x16x32_bf16 v[100:103], v[172:175], v[188:191], v[100:103]
	v_mfma_f32_16x16x32_bf16 v[84:87], v[172:175], v[210:213], v[84:87]
	v_mfma_f32_16x16x32_bf16 v[84:87], v[176:179], v[224:227], v[84:87]
	v_mfma_f32_16x16x32_bf16 v[68:71], v[176:179], v[240:243], v[68:71]
	v_mfma_f32_16x16x32_bf16 v[68:71], v[172:175], v[228:231], v[68:71]
	v_mfma_f32_16x16x32_bf16 v[72:75], v[164:167], v[228:231], v[72:75]
	v_mfma_f32_16x16x32_bf16 v[72:75], v[168:171], v[240:243], v[72:75]
	v_mfma_f32_16x16x32_bf16 v[88:91], v[168:171], v[224:227], v[88:91]
	v_mfma_f32_16x16x32_bf16 v[88:91], v[164:167], v[210:213], v[88:91]
	v_mfma_f32_16x16x32_bf16 v[104:107], v[164:167], v[188:191], v[104:107]
	v_mfma_f32_16x16x32_bf16 v[104:107], v[168:171], v[206:209], v[104:107]
	v_mfma_f32_16x16x32_bf16 v[120:123], v[168:171], v[184:187], v[120:123]
	v_mfma_f32_16x16x32_bf16 v[120:123], v[164:167], v[180:183], v[120:123]
	s_barrier
	s_add_i32 s18, s59, s35
	v_lshl_add_u64 v[192:193], v[192:193], 0, s[4:5]
	s_mov_b32 m0, s18
	ds_read_b128 v[180:183], v151 offset:49152
	ds_read_b128 v[184:187], v151 offset:50176
	ds_read_b128 v[188:191], v151 offset:51200
	ds_read_b128 v[206:209], v151 offset:52224
	ds_read_b128 v[210:213], v151 offset:53248
	ds_read_b128 v[224:227], v151 offset:54272
	ds_read_b128 v[228:231], v151 offset:55296
	ds_read_b128 v[240:243], v151 offset:56320
	global_load_lds_dwordx4 v[192:193], off
	s_add_i32 m0, s18, 0x2000
	s_add_u32 s14, s14, 0x100080
	v_lshl_add_u64 v[192:193], v[214:215], 0, s[4:5]
	s_addc_u32 s15, s15, 0
	s_add_i32 s18, s60, s35
	global_load_lds_dwordx4 v[192:193], off
	v_lshl_add_u64 v[192:193], s[14:15], 0, v[2:3]
	s_mov_b32 m0, s18
	s_nop 0
	global_load_lds_dwordx4 v[192:193], off
	v_lshl_add_u64 v[192:193], s[14:15], 0, v[132:133]
	s_add_i32 m0, s18, 0x2000
	s_nop 0
	global_load_lds_dwordx4 v[192:193], off
	v_lshl_add_u64 v[192:193], v[244:245], 0, s[4:5]
	s_mov_b32 m0, s56
	s_nop 0
	global_load_lds_dwordx4 v[192:193], off
	v_lshl_add_u64 v[192:193], v[246:247], 0, s[4:5]
	s_mov_b32 m0, s57
	s_nop 0
	global_load_lds_dwordx4 v[192:193], off
	s_waitcnt vmcnt(8)
	s_waitcnt lgkmcnt(0)
	s_barrier
	s_waitcnt lgkmcnt(0)
	v_mfma_f32_16x16x32_bf16 v[64:67], v[144:147], v[180:183], v[64:67]
	v_mfma_f32_16x16x32_bf16 v[64:67], v[152:155], v[184:187], v[64:67]
	v_mfma_f32_16x16x32_bf16 v[48:51], v[152:155], v[206:209], v[48:51]
	v_mfma_f32_16x16x32_bf16 v[48:51], v[144:147], v[188:191], v[48:51]
	v_mfma_f32_16x16x32_bf16 v[32:35], v[144:147], v[210:213], v[32:35]
	v_mfma_f32_16x16x32_bf16 v[32:35], v[152:155], v[224:227], v[32:35]
	v_mfma_f32_16x16x32_bf16 v[16:19], v[152:155], v[240:243], v[16:19]
	v_mfma_f32_16x16x32_bf16 v[16:19], v[144:147], v[228:231], v[16:19]
	v_mfma_f32_16x16x32_bf16 v[12:15], v[156:159], v[228:231], v[12:15]
	v_mfma_f32_16x16x32_bf16 v[12:15], v[160:163], v[240:243], v[12:15]
	v_mfma_f32_16x16x32_bf16 v[28:31], v[160:163], v[224:227], v[28:31]
	v_mfma_f32_16x16x32_bf16 v[28:31], v[156:159], v[210:213], v[28:31]
	v_mfma_f32_16x16x32_bf16 v[44:47], v[156:159], v[188:191], v[44:47]
	v_mfma_f32_16x16x32_bf16 v[44:47], v[160:163], v[206:209], v[44:47]
	v_mfma_f32_16x16x32_bf16 v[60:63], v[160:163], v[184:187], v[60:63]
	v_mfma_f32_16x16x32_bf16 v[60:63], v[156:159], v[180:183], v[60:63]
	v_mfma_f32_16x16x32_bf16 v[52:55], v[172:175], v[180:183], v[52:55]
	v_mfma_f32_16x16x32_bf16 v[52:55], v[176:179], v[184:187], v[52:55]
	v_mfma_f32_16x16x32_bf16 v[36:39], v[176:179], v[206:209], v[36:39]
	v_mfma_f32_16x16x32_bf16 v[36:39], v[172:175], v[188:191], v[36:39]
	v_mfma_f32_16x16x32_bf16 v[20:23], v[172:175], v[210:213], v[20:23]
	v_mfma_f32_16x16x32_bf16 v[20:23], v[176:179], v[224:227], v[20:23]
	v_mfma_f32_16x16x32_bf16 v[4:7], v[176:179], v[240:243], v[4:7]
	v_mfma_f32_16x16x32_bf16 v[4:7], v[172:175], v[228:231], v[4:7]
	v_mfma_f32_16x16x32_bf16 v[8:11], v[164:167], v[228:231], v[8:11]
	v_mfma_f32_16x16x32_bf16 v[8:11], v[168:171], v[240:243], v[8:11]
	v_mfma_f32_16x16x32_bf16 v[24:27], v[168:171], v[224:227], v[24:27]
	v_mfma_f32_16x16x32_bf16 v[24:27], v[164:167], v[210:213], v[24:27]
	v_mfma_f32_16x16x32_bf16 v[40:43], v[164:167], v[188:191], v[40:43]
	v_mfma_f32_16x16x32_bf16 v[40:43], v[168:171], v[206:209], v[40:43]
	v_mfma_f32_16x16x32_bf16 v[56:59], v[168:171], v[184:187], v[56:59]
	v_mfma_f32_16x16x32_bf16 v[56:59], v[164:167], v[180:183], v[56:59]
	s_barrier
	s_add_i32 s47, s47, 2
	s_add_u32 s52, s52, 0x100
	s_addc_u32 s53, s53, 0
	s_add_u32 s29, s29, 0x100
	s_addc_u32 s45, s45, 0
	s_cmp_gt_u32 s47, 61
	s_cbranch_scc0 .LBB0_1158
	s_and_b64 vcc, exec, s[42:43]
	s_cbranch_vccz .LBB0_1161
	s_barrier

.LBB0_1237:
	s_add_u32 s14, s52, 0x10000
	s_addc_u32 s15, s53, 0
	s_add_i32 s59, 0, 0x10000
	s_cmpk_eq_i32 s58, 0xa8
	s_cselect_b32 s25, s43, s15
	s_cselect_b32 s24, s42, s14
	s_cselect_b32 s19, s47, s57
	s_cselect_b32 s18, s46, s56
	s_add_i32 s60, 0, 0x14000
	v_add_u32_e32 v80, s59, v197
	v_add_u32_e32 v160, s60, v197
	ds_read_b128 v[60:63], v80
	ds_read_b128 v[68:71], v80 offset:1024
	ds_read_b128 v[76:79], v80 offset:2048
	ds_read_b128 v[80:83], v80 offset:3072
	ds_read_b128 v[148:151], v160
	ds_read_b128 v[152:155], v160 offset:1024
	ds_read_b128 v[156:159], v160 offset:2048
	ds_read_b128 v[160:163], v160 offset:3072
	v_lshl_add_u64 v[184:185], s[52:53], 0, v[188:189]
	s_add_i32 m0, s28, 0xc000
	ds_read_b128 v[164:167], v241
	ds_read_b128 v[168:171], v241 offset:1024
	ds_read_b128 v[172:175], v241 offset:2048
	ds_read_b128 v[176:179], v241 offset:3072
	ds_read_b128 v[180:183], v241 offset:4096
	ds_read_b128 v[206:209], v241 offset:5120
	ds_read_b128 v[210:213], v241 offset:6144
	ds_read_b128 v[224:227], v241 offset:7168
	global_load_lds_dwordx4 v[184:185], off
	v_lshl_add_u64 v[184:185], s[52:53], 0, v[190:191]
	s_add_i32 m0, s28, 0xe000
	s_nop 0
	global_load_lds_dwordx4 v[184:185], off
	s_waitcnt vmcnt(8)
	s_waitcnt lgkmcnt(0)
	s_barrier
	s_waitcnt lgkmcnt(0)
	v_mfma_f32_16x16x32_bf16 v[144:147], v[60:63], v[164:167], v[144:147]
	v_mfma_f32_16x16x32_bf16 v[144:147], v[68:71], v[168:171], v[144:147]
	v_mfma_f32_16x16x32_bf16 v[128:131], v[68:71], v[176:179], v[128:131]
	v_mfma_f32_16x16x32_bf16 v[128:131], v[60:63], v[172:175], v[128:131]
	v_mfma_f32_16x16x32_bf16 v[112:115], v[60:63], v[180:183], v[112:115]
	v_mfma_f32_16x16x32_bf16 v[112:115], v[68:71], v[206:209], v[112:115]
	v_mfma_f32_16x16x32_bf16 v[96:99], v[68:71], v[224:227], v[96:99]
	v_mfma_f32_16x16x32_bf16 v[96:99], v[60:63], v[210:213], v[96:99]
	v_mfma_f32_16x16x32_bf16 v[92:95], v[76:79], v[210:213], v[92:95]
	v_mfma_f32_16x16x32_bf16 v[92:95], v[80:83], v[224:227], v[92:95]
	v_mfma_f32_16x16x32_bf16 v[108:111], v[80:83], v[206:209], v[108:111]
	v_mfma_f32_16x16x32_bf16 v[108:111], v[76:79], v[180:183], v[108:111]
	v_mfma_f32_16x16x32_bf16 v[124:127], v[76:79], v[172:175], v[124:127]
	v_mfma_f32_16x16x32_bf16 v[124:127], v[80:83], v[176:179], v[124:127]
	v_mfma_f32_16x16x32_bf16 v[140:143], v[80:83], v[168:171], v[140:143]
	v_mfma_f32_16x16x32_bf16 v[140:143], v[76:79], v[164:167], v[140:143]
	v_mfma_f32_16x16x32_bf16 v[132:135], v[156:159], v[164:167], v[132:135]
	v_mfma_f32_16x16x32_bf16 v[132:135], v[160:163], v[168:171], v[132:135]
	v_mfma_f32_16x16x32_bf16 v[116:119], v[160:163], v[176:179], v[116:119]
	v_mfma_f32_16x16x32_bf16 v[116:119], v[156:159], v[172:175], v[116:119]
	v_mfma_f32_16x16x32_bf16 v[100:103], v[156:159], v[180:183], v[100:103]
	v_mfma_f32_16x16x32_bf16 v[100:103], v[160:163], v[206:209], v[100:103]
	v_mfma_f32_16x16x32_bf16 v[84:87], v[160:163], v[224:227], v[84:87]
	v_mfma_f32_16x16x32_bf16 v[84:87], v[156:159], v[210:213], v[84:87]
	v_mfma_f32_16x16x32_bf16 v[88:91], v[148:151], v[210:213], v[88:91]
	v_mfma_f32_16x16x32_bf16 v[88:91], v[152:155], v[224:227], v[88:91]
	v_mfma_f32_16x16x32_bf16 v[104:107], v[152:155], v[206:209], v[104:107]
	v_mfma_f32_16x16x32_bf16 v[104:107], v[148:151], v[180:183], v[104:107]
	v_mfma_f32_16x16x32_bf16 v[120:123], v[148:151], v[172:175], v[120:123]
	v_mfma_f32_16x16x32_bf16 v[120:123], v[152:155], v[176:179], v[120:123]
	v_mfma_f32_16x16x32_bf16 v[136:139], v[152:155], v[168:171], v[136:139]
	v_mfma_f32_16x16x32_bf16 v[136:139], v[148:151], v[164:167], v[136:139]
	s_barrier
	s_add_i32 s52, s59, s27
	v_lshl_add_u64 v[184:185], s[18:19], 0, v[2:3]
	s_mov_b32 m0, s52
	ds_read_b128 v[164:167], v241 offset:16384
	ds_read_b128 v[168:171], v241 offset:17408
	ds_read_b128 v[172:175], v241 offset:18432
	ds_read_b128 v[176:179], v241 offset:19456
	ds_read_b128 v[180:183], v241 offset:20480
	ds_read_b128 v[206:209], v241 offset:21504
	ds_read_b128 v[210:213], v241 offset:22528
	ds_read_b128 v[224:227], v241 offset:23552
	global_load_lds_dwordx4 v[184:185], off
	s_add_i32 m0, s52, 0x2000
	s_add_u32 s52, s18, 0x4000
	v_lshl_add_u64 v[192:193], s[18:19], 0, v[186:187]
	s_addc_u32 s53, s19, 0
	s_add_i32 s59, s60, s27
	global_load_lds_dwordx4 v[192:193], off
	v_lshl_add_u64 v[214:215], s[52:53], 0, v[2:3]
	s_mov_b32 m0, s59
	v_lshl_add_u64 v[228:229], s[24:25], 0, v[186:187]
	global_load_lds_dwordx4 v[214:215], off
	v_lshl_add_u64 v[214:215], s[52:53], 0, v[186:187]
	s_add_i32 m0, s59, 0x2000
	s_nop 0
	global_load_lds_dwordx4 v[214:215], off
	v_lshl_add_u64 v[214:215], s[24:25], 0, v[2:3]
	s_mov_b32 m0, s28
	s_nop 0
	global_load_lds_dwordx4 v[214:215], off
	s_mov_b32 m0, s29
	s_nop 0
	global_load_lds_dwordx4 v[228:229], off
	s_waitcnt vmcnt(8)
	s_waitcnt lgkmcnt(0)
	s_barrier
	s_waitcnt lgkmcnt(0)
	v_mfma_f32_16x16x32_bf16 v[72:75], v[60:63], v[164:167], v[72:75]
	v_mfma_f32_16x16x32_bf16 v[72:75], v[68:71], v[168:171], v[72:75]
	v_mfma_f32_16x16x32_bf16 v[48:51], v[68:71], v[176:179], v[48:51]
	v_mfma_f32_16x16x32_bf16 v[48:51], v[60:63], v[172:175], v[48:51]
	v_mfma_f32_16x16x32_bf16 v[32:35], v[60:63], v[180:183], v[32:35]
	v_mfma_f32_16x16x32_bf16 v[32:35], v[68:71], v[206:209], v[32:35]
	v_mfma_f32_16x16x32_bf16 v[16:19], v[68:71], v[224:227], v[16:19]
	v_mfma_f32_16x16x32_bf16 v[16:19], v[60:63], v[210:213], v[16:19]
	v_mfma_f32_16x16x32_bf16 v[12:15], v[76:79], v[210:213], v[12:15]
	v_mfma_f32_16x16x32_bf16 v[12:15], v[80:83], v[224:227], v[12:15]
	v_mfma_f32_16x16x32_bf16 v[28:31], v[80:83], v[206:209], v[28:31]
	v_mfma_f32_16x16x32_bf16 v[28:31], v[76:79], v[180:183], v[28:31]
	v_mfma_f32_16x16x32_bf16 v[44:47], v[76:79], v[172:175], v[44:47]
	v_mfma_f32_16x16x32_bf16 v[44:47], v[80:83], v[176:179], v[44:47]
	v_mfma_f32_16x16x32_bf16 v[64:67], v[80:83], v[168:171], v[64:67]
	v_mfma_f32_16x16x32_bf16 v[64:67], v[76:79], v[164:167], v[64:67]
	v_mfma_f32_16x16x32_bf16 v[52:55], v[156:159], v[164:167], v[52:55]
	v_mfma_f32_16x16x32_bf16 v[52:55], v[160:163], v[168:171], v[52:55]
	v_mfma_f32_16x16x32_bf16 v[36:39], v[160:163], v[176:179], v[36:39]
	v_mfma_f32_16x16x32_bf16 v[36:39], v[156:159], v[172:175], v[36:39]
	v_mfma_f32_16x16x32_bf16 v[20:23], v[156:159], v[180:183], v[20:23]
	v_mfma_f32_16x16x32_bf16 v[20:23], v[160:163], v[206:209], v[20:23]
	v_mfma_f32_16x16x32_bf16 v[4:7], v[160:163], v[224:227], v[4:7]
	v_mfma_f32_16x16x32_bf16 v[4:7], v[156:159], v[210:213], v[4:7]
	v_mfma_f32_16x16x32_bf16 v[8:11], v[148:151], v[210:213], v[8:11]
	v_mfma_f32_16x16x32_bf16 v[8:11], v[152:155], v[224:227], v[8:11]
	v_mfma_f32_16x16x32_bf16 v[24:27], v[152:155], v[206:209], v[24:27]
	v_mfma_f32_16x16x32_bf16 v[24:27], v[148:151], v[180:183], v[24:27]
	v_mfma_f32_16x16x32_bf16 v[40:43], v[148:151], v[172:175], v[40:43]
	v_mfma_f32_16x16x32_bf16 v[40:43], v[152:155], v[176:179], v[40:43]
	v_mfma_f32_16x16x32_bf16 v[56:59], v[152:155], v[168:171], v[56:59]
	v_mfma_f32_16x16x32_bf16 v[56:59], v[148:151], v[164:167], v[56:59]
	s_barrier
	s_add_i32 s52, 0, 0x18000
	s_add_i32 s53, 0, 0x1c000
	v_add_u32_e32 v80, s52, v197
	v_add_u32_e32 v160, s53, v197
	ds_read_b128 v[60:63], v80
	ds_read_b128 v[68:71], v80 offset:1024
	ds_read_b128 v[76:79], v80 offset:2048
	ds_read_b128 v[80:83], v80 offset:3072
	ds_read_b128 v[148:151], v160
	ds_read_b128 v[152:155], v160 offset:1024
	ds_read_b128 v[156:159], v160 offset:2048
	ds_read_b128 v[160:163], v160 offset:3072
	s_add_u32 s24, s24, 0x4000
	s_addc_u32 s25, s25, 0
	s_mov_b32 m0, s30
	v_lshl_add_u64 v[230:231], s[24:25], 0, v[2:3]
	ds_read_b128 v[164:167], v241 offset:32768
	ds_read_b128 v[168:171], v241 offset:33792
	ds_read_b128 v[172:175], v241 offset:34816
	ds_read_b128 v[176:179], v241 offset:35840
	ds_read_b128 v[180:183], v241 offset:36864
	ds_read_b128 v[206:209], v241 offset:37888
	ds_read_b128 v[210:213], v241 offset:38912
	ds_read_b128 v[224:227], v241 offset:39936
	global_load_lds_dwordx4 v[230:231], off
	v_lshl_add_u64 v[230:231], s[24:25], 0, v[186:187]
	s_mov_b32 m0, s31
	s_nop 0
	global_load_lds_dwordx4 v[230:231], off
	s_waitcnt vmcnt(8)
	s_waitcnt lgkmcnt(0)
	s_barrier
	s_waitcnt lgkmcnt(0)
	v_mfma_f32_16x16x32_bf16 v[144:147], v[60:63], v[164:167], v[144:147]
	v_mfma_f32_16x16x32_bf16 v[144:147], v[68:71], v[168:171], v[144:147]
	v_mfma_f32_16x16x32_bf16 v[128:131], v[68:71], v[176:179], v[128:131]
	v_mfma_f32_16x16x32_bf16 v[128:131], v[60:63], v[172:175], v[128:131]
	v_mfma_f32_16x16x32_bf16 v[112:115], v[60:63], v[180:183], v[112:115]
	v_mfma_f32_16x16x32_bf16 v[112:115], v[68:71], v[206:209], v[112:115]
	v_mfma_f32_16x16x32_bf16 v[96:99], v[68:71], v[224:227], v[96:99]
	v_mfma_f32_16x16x32_bf16 v[96:99], v[60:63], v[210:213], v[96:99]
	v_mfma_f32_16x16x32_bf16 v[92:95], v[76:79], v[210:213], v[92:95]
	v_mfma_f32_16x16x32_bf16 v[92:95], v[80:83], v[224:227], v[92:95]
	v_mfma_f32_16x16x32_bf16 v[108:111], v[80:83], v[206:209], v[108:111]
	v_mfma_f32_16x16x32_bf16 v[108:111], v[76:79], v[180:183], v[108:111]
	v_mfma_f32_16x16x32_bf16 v[124:127], v[76:79], v[172:175], v[124:127]
	v_mfma_f32_16x16x32_bf16 v[124:127], v[80:83], v[176:179], v[124:127]
	v_mfma_f32_16x16x32_bf16 v[140:143], v[80:83], v[168:171], v[140:143]
	v_mfma_f32_16x16x32_bf16 v[140:143], v[76:79], v[164:167], v[140:143]
	v_mfma_f32_16x16x32_bf16 v[132:135], v[156:159], v[164:167], v[132:135]
	v_mfma_f32_16x16x32_bf16 v[132:135], v[160:163], v[168:171], v[132:135]
	v_mfma_f32_16x16x32_bf16 v[116:119], v[160:163], v[176:179], v[116:119]
	v_mfma_f32_16x16x32_bf16 v[116:119], v[156:159], v[172:175], v[116:119]
	v_mfma_f32_16x16x32_bf16 v[100:103], v[156:159], v[180:183], v[100:103]
	v_mfma_f32_16x16x32_bf16 v[100:103], v[160:163], v[206:209], v[100:103]
	v_mfma_f32_16x16x32_bf16 v[84:87], v[160:163], v[224:227], v[84:87]
	v_mfma_f32_16x16x32_bf16 v[84:87], v[156:159], v[210:213], v[84:87]
	v_mfma_f32_16x16x32_bf16 v[88:91], v[148:151], v[210:213], v[88:91]
	v_mfma_f32_16x16x32_bf16 v[88:91], v[152:155], v[224:227], v[88:91]
	v_mfma_f32_16x16x32_bf16 v[104:107], v[152:155], v[206:209], v[104:107]
	v_mfma_f32_16x16x32_bf16 v[104:107], v[148:151], v[180:183], v[104:107]
	v_mfma_f32_16x16x32_bf16 v[120:123], v[148:151], v[172:175], v[120:123]
	v_mfma_f32_16x16x32_bf16 v[120:123], v[152:155], v[176:179], v[120:123]
	v_mfma_f32_16x16x32_bf16 v[136:139], v[152:155], v[168:171], v[136:139]
	v_mfma_f32_16x16x32_bf16 v[136:139], v[148:151], v[164:167], v[136:139]
	s_barrier
	s_add_i32 s24, s52, s27
	v_lshl_add_u64 v[184:185], v[184:185], 0, s[96:97]
	s_mov_b32 m0, s24
	ds_read_b128 v[164:167], v241 offset:49152
	ds_read_b128 v[168:171], v241 offset:50176
	ds_read_b128 v[172:175], v241 offset:51200
	ds_read_b128 v[176:179], v241 offset:52224
	ds_read_b128 v[180:183], v241 offset:53248
	ds_read_b128 v[206:209], v241 offset:54272
	ds_read_b128 v[210:213], v241 offset:55296
	ds_read_b128 v[224:227], v241 offset:56320
	global_load_lds_dwordx4 v[184:185], off
	s_add_i32 m0, s24, 0x2000
	s_add_u32 s18, s18, 0xc000
	v_lshl_add_u64 v[184:185], v[192:193], 0, s[96:97]
	s_addc_u32 s19, s19, 0
	s_add_i32 s24, s53, s27
	global_load_lds_dwordx4 v[184:185], off
	v_lshl_add_u64 v[184:185], s[18:19], 0, v[2:3]
	s_mov_b32 m0, s24
	s_nop 0
	global_load_lds_dwordx4 v[184:185], off
	v_lshl_add_u64 v[184:185], s[18:19], 0, v[186:187]
	s_add_i32 m0, s24, 0x2000
	s_nop 0
	global_load_lds_dwordx4 v[184:185], off
	v_lshl_add_u64 v[184:185], v[214:215], 0, s[96:97]
	s_mov_b32 m0, s35
	s_nop 0
	global_load_lds_dwordx4 v[184:185], off
	v_lshl_add_u64 v[184:185], v[228:229], 0, s[96:97]
	s_mov_b32 m0, s36
	s_nop 0
	global_load_lds_dwordx4 v[184:185], off
	s_waitcnt vmcnt(8)
	s_waitcnt lgkmcnt(0)
	s_barrier
	s_waitcnt lgkmcnt(0)
	v_mfma_f32_16x16x32_bf16 v[72:75], v[60:63], v[164:167], v[72:75]
	v_mfma_f32_16x16x32_bf16 v[72:75], v[68:71], v[168:171], v[72:75]
	v_mfma_f32_16x16x32_bf16 v[48:51], v[68:71], v[176:179], v[48:51]
	v_mfma_f32_16x16x32_bf16 v[48:51], v[60:63], v[172:175], v[48:51]
	v_mfma_f32_16x16x32_bf16 v[32:35], v[60:63], v[180:183], v[32:35]
	v_mfma_f32_16x16x32_bf16 v[32:35], v[68:71], v[206:209], v[32:35]
	v_mfma_f32_16x16x32_bf16 v[16:19], v[68:71], v[224:227], v[16:19]
	v_mfma_f32_16x16x32_bf16 v[16:19], v[60:63], v[210:213], v[16:19]
	v_mfma_f32_16x16x32_bf16 v[12:15], v[76:79], v[210:213], v[12:15]
	v_mfma_f32_16x16x32_bf16 v[12:15], v[80:83], v[224:227], v[12:15]
	v_mfma_f32_16x16x32_bf16 v[28:31], v[80:83], v[206:209], v[28:31]
	v_mfma_f32_16x16x32_bf16 v[28:31], v[76:79], v[180:183], v[28:31]
	v_mfma_f32_16x16x32_bf16 v[44:47], v[76:79], v[172:175], v[44:47]
	v_mfma_f32_16x16x32_bf16 v[44:47], v[80:83], v[176:179], v[44:47]
	v_mfma_f32_16x16x32_bf16 v[64:67], v[80:83], v[168:171], v[64:67]
	v_mfma_f32_16x16x32_bf16 v[64:67], v[76:79], v[164:167], v[64:67]
	v_mfma_f32_16x16x32_bf16 v[52:55], v[156:159], v[164:167], v[52:55]
	v_mfma_f32_16x16x32_bf16 v[52:55], v[160:163], v[168:171], v[52:55]
	v_mfma_f32_16x16x32_bf16 v[36:39], v[160:163], v[176:179], v[36:39]
	v_mfma_f32_16x16x32_bf16 v[36:39], v[156:159], v[172:175], v[36:39]
	v_mfma_f32_16x16x32_bf16 v[20:23], v[156:159], v[180:183], v[20:23]
	v_mfma_f32_16x16x32_bf16 v[20:23], v[160:163], v[206:209], v[20:23]
	v_mfma_f32_16x16x32_bf16 v[4:7], v[160:163], v[224:227], v[4:7]
	v_mfma_f32_16x16x32_bf16 v[4:7], v[156:159], v[210:213], v[4:7]
	v_mfma_f32_16x16x32_bf16 v[8:11], v[148:151], v[210:213], v[8:11]
	v_mfma_f32_16x16x32_bf16 v[8:11], v[152:155], v[224:227], v[8:11]
	v_mfma_f32_16x16x32_bf16 v[24:27], v[152:155], v[206:209], v[24:27]
	v_mfma_f32_16x16x32_bf16 v[24:27], v[148:151], v[180:183], v[24:27]
	v_mfma_f32_16x16x32_bf16 v[40:43], v[148:151], v[172:175], v[40:43]
	v_mfma_f32_16x16x32_bf16 v[40:43], v[152:155], v[176:179], v[40:43]
	v_mfma_f32_16x16x32_bf16 v[56:59], v[152:155], v[168:171], v[56:59]
	v_mfma_f32_16x16x32_bf16 v[56:59], v[148:151], v[164:167], v[56:59]
	s_barrier
	s_add_i32 s58, s58, 2
	s_add_u32 s56, s56, 0x10000
	s_addc_u32 s57, s57, 0
	s_cmpk_gt_u32 s58, 0xa9
	s_mov_b64 s[52:53], s[14:15]
	s_cbranch_scc0 .LBB0_1237
	s_and_b64 vcc, exec, s[44:45]
	s_cbranch_vccz .LBB0_1240
	s_barrier
